# GEMM K loop: the A DMAs of a stage share one M0 (LDS-DMA instruction offsets), second B DMA via a lowered base: 2 M0 writes per iteration instead of 6
# baseline (speedup 1.0000x reference)
.LBB0_245:
	v_add_u32_e32 v130, 0xfffffc00, v130
	v_add_u32_e32 v132, 0xfffff800, v132
	v_add_u32_e32 v136, 0xfffff400, v136
	s_and_b32 s9, s76, 7
	s_add_u32 s5, s58, s50
	s_addc_u32 s6, s59, s51
	s_lshl_b32 s8, s8, 3
	s_or_b32 s8, s8, s9
	s_lshl_b32 s7, s7, 3
	s_sub_i32 s7, s8, s7
	s_lshl_b32 s8, s7, 8
	s_ashr_i32 s9, s8, 31
	s_lshl_b64 s[8:9], s[8:9], 11
	s_add_u32 s8, s56, s8
	v_mov_b32_e32 v2, 0
	s_addc_u32 s9, s57, s9
	s_mov_b32 s7, 0
	s_mov_b64 s[50:51], 0
	s_mov_b32 s100, 0
	v_mov_b32_e32 v3, v2
	v_mov_b32_e32 v4, v2
	v_mov_b32_e32 v5, v2
	v_mov_b32_e32 v6, v2
	v_mov_b32_e32 v7, v2
	v_mov_b32_e32 v8, v2
	v_mov_b32_e32 v9, v2
	v_mov_b32_e32 v10, v2
	v_mov_b32_e32 v11, v2
	v_mov_b32_e32 v12, v2
	v_mov_b32_e32 v13, v2
	v_mov_b32_e32 v14, v2
	v_mov_b32_e32 v15, v2
	v_mov_b32_e32 v16, v2
	v_mov_b32_e32 v17, v2
	v_mov_b32_e32 v22, v2
	v_mov_b32_e32 v23, v2
	v_mov_b32_e32 v24, v2
	v_mov_b32_e32 v25, v2
	v_mov_b32_e32 v30, v2
	v_mov_b32_e32 v31, v2
	v_mov_b32_e32 v32, v2
	v_mov_b32_e32 v33, v2
	v_mov_b32_e32 v38, v2
	v_mov_b32_e32 v39, v2
	v_mov_b32_e32 v40, v2
	v_mov_b32_e32 v41, v2
	v_mov_b32_e32 v46, v2
	v_mov_b32_e32 v47, v2
	v_mov_b32_e32 v48, v2
	v_mov_b32_e32 v49, v2
	v_mov_b32_e32 v18, v2
	v_mov_b32_e32 v19, v2
	v_mov_b32_e32 v20, v2
	v_mov_b32_e32 v21, v2
	v_mov_b32_e32 v26, v2
	v_mov_b32_e32 v27, v2
	v_mov_b32_e32 v28, v2
	v_mov_b32_e32 v29, v2
	v_mov_b32_e32 v34, v2
	v_mov_b32_e32 v35, v2
	v_mov_b32_e32 v36, v2
	v_mov_b32_e32 v37, v2
	v_mov_b32_e32 v42, v2
	v_mov_b32_e32 v43, v2
	v_mov_b32_e32 v44, v2
	v_mov_b32_e32 v45, v2
	v_mov_b32_e32 v54, v2
	v_mov_b32_e32 v55, v2
	v_mov_b32_e32 v56, v2
	v_mov_b32_e32 v57, v2
	v_mov_b32_e32 v62, v2
	v_mov_b32_e32 v63, v2
	v_mov_b32_e32 v64, v2
	v_mov_b32_e32 v65, v2
	v_mov_b32_e32 v70, v2
	v_mov_b32_e32 v71, v2
	v_mov_b32_e32 v72, v2
	v_mov_b32_e32 v73, v2
	v_mov_b32_e32 v78, v2
	v_mov_b32_e32 v79, v2
	v_mov_b32_e32 v80, v2
	v_mov_b32_e32 v81, v2
	v_mov_b32_e32 v50, v2
	v_mov_b32_e32 v51, v2
	v_mov_b32_e32 v52, v2
	v_mov_b32_e32 v53, v2
	v_mov_b32_e32 v58, v2
	v_mov_b32_e32 v59, v2
	v_mov_b32_e32 v60, v2
	v_mov_b32_e32 v61, v2
	v_mov_b32_e32 v66, v2
	v_mov_b32_e32 v67, v2
	v_mov_b32_e32 v68, v2
	v_mov_b32_e32 v69, v2
	v_mov_b32_e32 v74, v2
	v_mov_b32_e32 v75, v2
	v_mov_b32_e32 v76, v2
	v_mov_b32_e32 v77, v2
	v_mov_b32_e32 v86, v2
	v_mov_b32_e32 v87, v2
	v_mov_b32_e32 v88, v2
	v_mov_b32_e32 v89, v2
	v_mov_b32_e32 v94, v2
	v_mov_b32_e32 v95, v2
	v_mov_b32_e32 v96, v2
	v_mov_b32_e32 v97, v2
	v_mov_b32_e32 v102, v2
	v_mov_b32_e32 v103, v2
	v_mov_b32_e32 v104, v2
	v_mov_b32_e32 v105, v2
	v_mov_b32_e32 v110, v2
	v_mov_b32_e32 v111, v2
	v_mov_b32_e32 v112, v2
	v_mov_b32_e32 v113, v2
	v_mov_b32_e32 v82, v2
	v_mov_b32_e32 v83, v2
	v_mov_b32_e32 v84, v2
	v_mov_b32_e32 v85, v2
	v_mov_b32_e32 v90, v2
	v_mov_b32_e32 v91, v2
	v_mov_b32_e32 v92, v2
	v_mov_b32_e32 v93, v2
	v_mov_b32_e32 v98, v2
	v_mov_b32_e32 v99, v2
	v_mov_b32_e32 v100, v2
	v_mov_b32_e32 v101, v2
	v_mov_b32_e32 v106, v2
	v_mov_b32_e32 v107, v2
	v_mov_b32_e32 v108, v2
	v_mov_b32_e32 v109, v2
	v_mov_b32_e32 v114, v2
	v_mov_b32_e32 v115, v2
	v_mov_b32_e32 v116, v2
	v_mov_b32_e32 v117, v2
	v_mov_b32_e32 v118, v2
	v_mov_b32_e32 v119, v2
	v_mov_b32_e32 v120, v2
	v_mov_b32_e32 v121, v2
	v_mov_b32_e32 v122, v2
	v_mov_b32_e32 v123, v2
	v_mov_b32_e32 v124, v2
	v_mov_b32_e32 v125, v2
	v_mov_b32_e32 v126, v2
	v_mov_b32_e32 v127, v2
	v_mov_b32_e32 v128, v2
	v_mov_b32_e32 v129, v2
.LBB0_246:
	s_add_i32 s10, s7, 0xffffa000
	s_cmp_lg_u32 s7, 0
	s_cselect_b32 s12, s10, 0xc000
	v_add_u32_e32 v131, s7, v150
	s_waitcnt vmcnt(6)
	s_barrier
	v_add_u32_e32 v133, s7, v149
	ds_read_b128 v[154:157], v131 offset:0
	ds_read_b128 v[158:161], v131 offset:0x400
	ds_read_b128 v[162:165], v131 offset:0x800
	ds_read_b128 v[166:169], v131 offset:0xc00
	v_add_u32_e32 v131, s12, v147
	ds_read_b128 v[170:173], v133 offset:0
	ds_read_b128 v[174:177], v133 offset:0x400
	ds_read_b128 v[178:181], v133 offset:0x800
	ds_read_b128 v[200:203], v133 offset:0xc00
	s_add_u32 s10, s8, s50
	s_addc_u32 s11, s9, s51
	v_readfirstlane_b32 s13, v131
	s_add_u32 s64, s5, s100
	s_addc_u32 s65, s6, 0
	s_add_u32 s70, s64, 0xfffffc00
	s_addc_u32 s71, s65, -1
	s_add_i32 s66, s7, 0x6000
	s_cmpk_lg_u32 s7, 0xc000
	s_cselect_b32 s7, s66, 0
	s_addk_i32 s100, 0x400
	s_add_u32 s50, s50, s60
	s_addc_u32 s51, s51, 0
	s_sub_i32 s68, s13, s12
	s_lshr_b32 s68, s68, 1
	s_add_i32 s68, s68, s12
	s_addk_i32 s68, 0x4000
	s_waitcnt lgkmcnt(0)
	v_mfma_f32_16x16x32_bf16 v[126:129], v[154:157], v[170:173], v[126:129]
	ds_read_b128 v[204:207], v133 offset:0x1000
	v_mfma_f32_16x16x32_bf16 v[122:125], v[154:157], v[174:177], v[122:125]
	ds_read_b128 v[208:211], v133 offset:0x1400
	v_mfma_f32_16x16x32_bf16 v[118:121], v[154:157], v[178:181], v[118:121]
	ds_read_b128 v[212:215], v133 offset:0x1800
	v_mfma_f32_16x16x32_bf16 v[114:117], v[154:157], v[200:203], v[114:117]
	ds_read_b128 v[216:219], v133 offset:0x1c00
	s_mov_b32 m0, s13
	v_mfma_f32_16x16x32_bf16 v[110:113], v[158:161], v[170:173], v[110:113]
	global_load_lds_dwordx4 v0, s[10:11]
	v_mfma_f32_16x16x32_bf16 v[102:105], v[158:161], v[174:177], v[102:105]
	v_mfma_f32_16x16x32_bf16 v[94:97], v[158:161], v[178:181], v[94:97]
	v_mfma_f32_16x16x32_bf16 v[86:89], v[158:161], v[200:203], v[86:89]
	global_load_lds_dwordx4 v130, s[10:11] offset:1024
	v_mfma_f32_16x16x32_bf16 v[78:81], v[162:165], v[170:173], v[78:81]
	v_mfma_f32_16x16x32_bf16 v[70:73], v[162:165], v[174:177], v[70:73]
	v_mfma_f32_16x16x32_bf16 v[62:65], v[162:165], v[178:181], v[62:65]
	global_load_lds_dwordx4 v132, s[10:11] offset:2048
	v_mfma_f32_16x16x32_bf16 v[54:57], v[162:165], v[200:203], v[54:57]
	v_mfma_f32_16x16x32_bf16 v[46:49], v[166:169], v[170:173], v[46:49]
	v_mfma_f32_16x16x32_bf16 v[38:41], v[166:169], v[174:177], v[38:41]
	global_load_lds_dwordx4 v136, s[10:11] offset:3072
	v_mfma_f32_16x16x32_bf16 v[30:33], v[166:169], v[178:181], v[30:33]
	v_mfma_f32_16x16x32_bf16 v[22:25], v[166:169], v[200:203], v[22:25]
	s_waitcnt lgkmcnt(0)
	v_mfma_f32_16x16x32_bf16 v[106:109], v[154:157], v[204:207], v[106:109]
	v_mfma_f32_16x16x32_bf16 v[98:101], v[154:157], v[208:211], v[98:101]
	s_mov_b32 m0, s68
	v_mfma_f32_16x16x32_bf16 v[90:93], v[154:157], v[212:215], v[90:93]
	global_load_lds_dwordx4 v138, s[64:65]
	v_mfma_f32_16x16x32_bf16 v[82:85], v[154:157], v[216:219], v[82:85]
	v_mfma_f32_16x16x32_bf16 v[74:77], v[158:161], v[204:207], v[74:77]
	v_mfma_f32_16x16x32_bf16 v[66:69], v[158:161], v[208:211], v[66:69]
	v_mfma_f32_16x16x32_bf16 v[58:61], v[158:161], v[212:215], v[58:61]
	v_mfma_f32_16x16x32_bf16 v[50:53], v[158:161], v[216:219], v[50:53]
	v_mfma_f32_16x16x32_bf16 v[42:45], v[162:165], v[204:207], v[42:45]
	global_load_lds_dwordx4 v140, s[70:71] offset:1024
	v_mfma_f32_16x16x32_bf16 v[34:37], v[162:165], v[208:211], v[34:37]
	v_mfma_f32_16x16x32_bf16 v[26:29], v[162:165], v[212:215], v[26:29]
	v_mfma_f32_16x16x32_bf16 v[18:21], v[162:165], v[216:219], v[18:21]
	v_mfma_f32_16x16x32_bf16 v[14:17], v[166:169], v[204:207], v[14:17]
	v_mfma_f32_16x16x32_bf16 v[10:13], v[166:169], v[208:211], v[10:13]
	v_mfma_f32_16x16x32_bf16 v[6:9], v[166:169], v[212:215], v[6:9]
	v_mfma_f32_16x16x32_bf16 v[2:5], v[166:169], v[216:219], v[2:5]
	s_cmpk_lg_i32 s100, 0x7800
	s_cbranch_scc1 .LBB0_246
	s_waitcnt vmcnt(6)
	s_barrier
	v_add_u32_e32 v0, s7, v150
	v_add_u32_e32 v140, s7, v149
	ds_read_b128 v[130:133], v0 offset:0
	ds_read_b128 v[136:139], v0 offset:0x400
	ds_read_b128 v[154:157], v0 offset:0x800
	ds_read_b128 v[158:161], v0 offset:0xc00
	ds_read_b128 v[162:165], v140 offset:0
	ds_read_b128 v[166:169], v140 offset:0x400
	ds_read_b128 v[170:173], v140 offset:0x800
	ds_read_b128 v[174:177], v140 offset:0xc00
	ds_read_b128 v[178:181], v140 offset:0x1000
	ds_read_b128 v[200:203], v140 offset:0x1400
	ds_read_b128 v[204:207], v140 offset:0x1800
	ds_read_b128 v[208:211], v140 offset:0x1c00
	s_lshl_b32 s49, s4, 8
	s_waitcnt lgkmcnt(4)
	s_nop 0
	v_mfma_f32_16x16x32_bf16 v[126:129], v[130:133], v[162:165], v[126:129]
	v_mfma_f32_16x16x32_bf16 v[118:121], v[130:133], v[170:173], v[118:121]
	v_mfma_f32_16x16x32_bf16 v[114:117], v[130:133], v[174:177], v[114:117]
	v_mfma_f32_16x16x32_bf16 v[110:113], v[136:139], v[162:165], v[110:113]
	v_mfma_f32_16x16x32_bf16 v[102:105], v[136:139], v[166:169], v[102:105]
	v_mfma_f32_16x16x32_bf16 v[94:97], v[136:139], v[170:173], v[94:97]
	v_mfma_f32_16x16x32_bf16 v[86:89], v[136:139], v[174:177], v[86:89]
	v_mfma_f32_16x16x32_bf16 v[70:73], v[154:157], v[166:169], v[70:73]
	v_mfma_f32_16x16x32_bf16 v[62:65], v[154:157], v[170:173], v[62:65]
	v_mfma_f32_16x16x32_bf16 v[54:57], v[154:157], v[174:177], v[54:57]
	v_mfma_f32_16x16x32_bf16 v[46:49], v[158:161], v[162:165], v[46:49]
	v_mfma_f32_16x16x32_bf16 v[38:41], v[158:161], v[166:169], v[38:41]
	v_mfma_f32_16x16x32_bf16 v[30:33], v[158:161], v[170:173], v[30:33]
	v_mfma_f32_16x16x32_bf16 v[22:25], v[158:161], v[174:177], v[22:25]
	v_mfma_f32_16x16x32_bf16 v[212:215], v[130:133], v[166:169], v[122:125]
	v_mfma_f32_16x16x32_bf16 v[216:219], v[154:157], v[162:165], v[78:81]
	s_waitcnt lgkmcnt(0)
	s_nop 0
	v_mfma_f32_16x16x32_bf16 v[174:177], v[136:139], v[178:181], v[74:77]
	v_mfma_f32_16x16x32_bf16 v[220:223], v[136:139], v[200:203], v[66:69]
	v_mfma_f32_16x16x32_bf16 v[224:227], v[136:139], v[204:207], v[58:61]
	v_mfma_f32_16x16x32_bf16 v[50:53], v[136:139], v[208:211], v[50:53]
	v_mfma_f32_16x16x32_bf16 v[136:139], v[154:157], v[178:181], v[42:45]
	v_mfma_f32_16x16x32_bf16 v[34:37], v[154:157], v[200:203], v[34:37]
	v_mfma_f32_16x16x32_bf16 v[6:9], v[158:161], v[204:207], v[6:9]
	v_mfma_f32_16x16x32_bf16 v[162:165], v[130:133], v[178:181], v[106:109]
	v_mfma_f32_16x16x32_bf16 v[166:169], v[130:133], v[200:203], v[98:101]
	v_mfma_f32_16x16x32_bf16 v[170:173], v[130:133], v[204:207], v[90:93]
	v_mfma_f32_16x16x32_bf16 v[130:133], v[130:133], v[208:211], v[82:85]
	v_mfma_f32_16x16x32_bf16 v[228:231], v[154:157], v[204:207], v[26:29]
	v_mfma_f32_16x16x32_bf16 v[154:157], v[154:157], v[208:211], v[18:21]
	v_mfma_f32_16x16x32_bf16 v[178:181], v[158:161], v[178:181], v[14:17]
	v_mfma_f32_16x16x32_bf16 v[200:203], v[158:161], v[200:203], v[10:13]
	v_mfma_f32_16x16x32_bf16 v[158:161], v[158:161], v[208:211], v[2:5]
	s_waitcnt vmcnt(0)
	s_barrier
	ds_read_b128 v[2:5], v151 offset:0
	ds_read_b128 v[14:17], v151 offset:0x400
	ds_read_b128 v[204:207], v151 offset:0x800
	ds_read_b128 v[208:211], v151 offset:0xc00
	ds_read_b128 v[10:13], v152 offset:0
	ds_read_b128 v[18:21], v152 offset:0x400
	ds_read_b128 v[26:29], v152 offset:0x800
	ds_read_b128 v[42:45], v152 offset:0xc00
	ds_read_b128 v[232:235], v152 offset:0x1000
	ds_read_b128 v[236:239], v152 offset:0x1400
	ds_read_b128 v[240:243], v152 offset:0x1800
	ds_read_b128 v[244:247], v152 offset:0x1c00
	s_nop 0
	s_waitcnt lgkmcnt(4)
	s_nop 0
	v_mfma_f32_16x16x32_bf16 v[122:125], v[2:5], v[10:13], v[126:129]
	v_mfma_f32_16x16x32_bf16 v[106:109], v[2:5], v[18:21], v[212:215]
	v_mfma_f32_16x16x32_bf16 v[90:93], v[2:5], v[26:29], v[118:121]
	v_mfma_f32_16x16x32_bf16 v[74:77], v[2:5], v[42:45], v[114:117]
	v_mfma_f32_16x16x32_bf16 v[126:129], v[14:17], v[10:13], v[110:113]
	v_mfma_f32_16x16x32_bf16 v[110:113], v[14:17], v[18:21], v[102:105]
	v_mfma_f32_16x16x32_bf16 v[94:97], v[14:17], v[26:29], v[94:97]
	v_mfma_f32_16x16x32_bf16 v[78:81], v[14:17], v[42:45], v[86:89]
	v_mfma_f32_16x16x32_bf16 v[114:117], v[204:207], v[10:13], v[216:219]
	v_mfma_f32_16x16x32_bf16 v[98:101], v[204:207], v[18:21], v[70:73]
	v_mfma_f32_16x16x32_bf16 v[82:85], v[204:207], v[26:29], v[62:65]
	v_mfma_f32_16x16x32_bf16 v[66:69], v[204:207], v[42:45], v[54:57]
	v_mfma_f32_16x16x32_bf16 v[118:121], v[208:211], v[10:13], v[46:49]
	v_mfma_f32_16x16x32_bf16 v[102:105], v[208:211], v[18:21], v[38:41]
	v_mfma_f32_16x16x32_bf16 v[86:89], v[208:211], v[26:29], v[30:33]
	v_mfma_f32_16x16x32_bf16 v[70:73], v[208:211], v[42:45], v[22:25]
	s_waitcnt lgkmcnt(0)
	s_nop 0
	v_mfma_f32_16x16x32_bf16 v[58:61], v[2:5], v[232:235], v[162:165]
	v_mfma_f32_16x16x32_bf16 v[42:45], v[2:5], v[236:239], v[166:169]
	v_mfma_f32_16x16x32_bf16 v[26:29], v[2:5], v[240:243], v[170:173]
	v_mfma_f32_16x16x32_bf16 v[10:13], v[2:5], v[244:247], v[130:133]
	v_mfma_f32_16x16x32_bf16 v[62:65], v[14:17], v[232:235], v[174:177]
	v_mfma_f32_16x16x32_bf16 v[46:49], v[14:17], v[236:239], v[220:223]
	v_mfma_f32_16x16x32_bf16 v[30:33], v[14:17], v[240:243], v[224:227]
	v_mfma_f32_16x16x32_bf16 v[14:17], v[14:17], v[244:247], v[50:53]
	v_mfma_f32_16x16x32_bf16 v[50:53], v[204:207], v[232:235], v[136:139]
	v_mfma_f32_16x16x32_bf16 v[34:37], v[204:207], v[236:239], v[34:37]
	v_mfma_f32_16x16x32_bf16 v[18:21], v[204:207], v[240:243], v[228:231]
	v_mfma_f32_16x16x32_bf16 v[2:5], v[204:207], v[244:247], v[154:157]
	v_mfma_f32_16x16x32_bf16 v[54:57], v[208:211], v[232:235], v[178:181]
	v_mfma_f32_16x16x32_bf16 v[38:41], v[208:211], v[236:239], v[200:203]
	v_mfma_f32_16x16x32_bf16 v[22:25], v[208:211], v[240:243], v[6:9]
	v_mfma_f32_16x16x32_bf16 v[6:9], v[208:211], v[244:247], v[158:161]
	v_mov_b32_e32 v136, v134
	s_mov_b64 s[50:51], -1
	s_and_b64 vcc, exec, s[22:23]
	s_barrier
	s_cbranch_vccz .LBB0_264
	s_and_b64 vcc, exec, s[0:1]
	s_cbranch_vccz .LBB0_250
	v_lshrrev_b32_e32 v0, 6, v136
	v_mul_lo_u32 v137, v0, s14
	v_and_b32_e32 v130, 15, v136
	v_and_or_b32 v0, v136, 48, v137
	s_movk_i32 s4, 0x90
	v_mad_u32_u24 v0, v130, s4, v0
	v_cvt_pk_bf16_f32 v130, v122, v123
	v_cvt_pk_bf16_f32 v131, v124, v125
	v_cvt_pk_bf16_f32 v132, v126, v127
	v_cvt_pk_bf16_f32 v133, v128, v129
	s_waitcnt vmcnt(0)
	ds_write_b128 v0, v[130:133]
	v_cvt_pk_bf16_f32 v130, v114, v115
	v_cvt_pk_bf16_f32 v131, v116, v117
	v_cvt_pk_bf16_f32 v132, v118, v119
	v_cvt_pk_bf16_f32 v133, v120, v121
	ds_write_b128 v0, v[130:133] offset:64
	v_cvt_pk_bf16_f32 v130, v106, v107
	v_cvt_pk_bf16_f32 v131, v108, v109
	v_cvt_pk_bf16_f32 v132, v110, v111
	v_cvt_pk_bf16_f32 v133, v112, v113
	ds_write_b128 v0, v[130:133] offset:2304
	v_cvt_pk_bf16_f32 v130, v98, v99
	v_cvt_pk_bf16_f32 v131, v100, v101
	v_cvt_pk_bf16_f32 v132, v102, v103
	v_cvt_pk_bf16_f32 v133, v104, v105
	ds_write_b128 v0, v[130:133] offset:2368
	v_cvt_pk_bf16_f32 v130, v90, v91
	v_cvt_pk_bf16_f32 v131, v92, v93
	v_cvt_pk_bf16_f32 v132, v94, v95
	v_cvt_pk_bf16_f32 v133, v96, v97
	ds_write_b128 v0, v[130:133] offset:4608
	v_cvt_pk_bf16_f32 v130, v82, v83
	v_cvt_pk_bf16_f32 v131, v84, v85
	v_cvt_pk_bf16_f32 v132, v86, v87
	v_cvt_pk_bf16_f32 v133, v88, v89
	ds_write_b128 v0, v[130:133] offset:4672
	v_cvt_pk_bf16_f32 v130, v74, v75
	v_cvt_pk_bf16_f32 v131, v76, v77
	v_cvt_pk_bf16_f32 v132, v78, v79
	v_cvt_pk_bf16_f32 v133, v80, v81
	ds_write_b128 v0, v[130:133] offset:6912
	v_cvt_pk_bf16_f32 v130, v66, v67
	v_cvt_pk_bf16_f32 v131, v68, v69
	v_cvt_pk_bf16_f32 v132, v70, v71
	v_cvt_pk_bf16_f32 v133, v72, v73
	ds_write_b128 v0, v[130:133] offset:6976
	v_cvt_pk_bf16_f32 v130, v58, v59
	v_cvt_pk_bf16_f32 v131, v60, v61
	v_cvt_pk_bf16_f32 v132, v62, v63
	v_cvt_pk_bf16_f32 v133, v64, v65
	ds_write_b128 v0, v[130:133] offset:9216
	v_cvt_pk_bf16_f32 v130, v50, v51
	v_cvt_pk_bf16_f32 v131, v52, v53
	v_cvt_pk_bf16_f32 v132, v54, v55
	v_cvt_pk_bf16_f32 v133, v56, v57
	ds_write_b128 v0, v[130:133] offset:9280
	v_cvt_pk_bf16_f32 v130, v42, v43
	v_cvt_pk_bf16_f32 v131, v44, v45
	v_cvt_pk_bf16_f32 v132, v46, v47
	v_cvt_pk_bf16_f32 v133, v48, v49
	ds_write_b128 v0, v[130:133] offset:11520
	v_cvt_pk_bf16_f32 v130, v34, v35
	v_cvt_pk_bf16_f32 v131, v36, v37
	v_cvt_pk_bf16_f32 v132, v38, v39
	v_cvt_pk_bf16_f32 v133, v40, v41
	ds_write_b128 v0, v[130:133] offset:11584
	v_cvt_pk_bf16_f32 v130, v26, v27
	v_cvt_pk_bf16_f32 v131, v28, v29
	v_cvt_pk_bf16_f32 v132, v30, v31
	v_cvt_pk_bf16_f32 v133, v32, v33
	ds_write_b128 v0, v[130:133] offset:13824
	v_cvt_pk_bf16_f32 v130, v18, v19
	v_cvt_pk_bf16_f32 v131, v20, v21
	v_cvt_pk_bf16_f32 v132, v22, v23
	v_cvt_pk_bf16_f32 v133, v24, v25
	ds_write_b128 v0, v[130:133] offset:13888
	v_cvt_pk_bf16_f32 v130, v10, v11
	v_cvt_pk_bf16_f32 v131, v12, v13
	v_cvt_pk_bf16_f32 v132, v14, v15
	v_cvt_pk_bf16_f32 v133, v16, v17
	ds_write_b128 v0, v[130:133] offset:16128
	v_cvt_pk_bf16_f32 v130, v2, v3
	v_cvt_pk_bf16_f32 v131, v4, v5
	v_cvt_pk_bf16_f32 v132, v6, v7
	v_cvt_pk_bf16_f32 v133, v8, v9
	ds_write_b128 v0, v[130:133] offset:16192
	v_and_b32_e32 v0, 0xffffff80, v136
	v_add_u32_e32 v130, s48, v0
	v_ashrrev_i32_e32 v131, 31, v130
	v_lshlrev_b64 v[130:131], 11, v[130:131]
	v_lshl_add_u64 v[130:131], s[38:39], 0, v[130:131]
	v_and_b32_e32 v0, 64, v136
	v_lshl_add_u64 v[130:131], s[46:47], 1, v[130:131]
	v_lshlrev_b32_e32 v0, 1, v0
	v_lshl_add_u64 v[138:139], v[130:131], 0, v[0:1]
	v_lshlrev_b32_e32 v0, 4, v136
	v_and_b32_e32 v0, 0x70, v0
	v_bfe_u32 v140, v136, 3, 3
	v_or_b32_e32 v130, v137, v0
	s_waitcnt lgkmcnt(0)
	v_mad_u32_u24 v137, v140, s4, v130
	ds_read_b128 v[66:69], v137
	ds_read_b128 v[70:73], v137 offset:1152
	ds_read_b128 v[74:77], v137 offset:2304
	ds_read_b128 v[78:81], v137 offset:3456
	ds_read_b128 v[82:85], v137 offset:4608
	ds_read_b128 v[86:89], v137 offset:5760
	ds_read_b128 v[90:93], v137 offset:6912
	ds_read_b128 v[94:97], v137 offset:8064
	ds_read_b128 v[98:101], v137 offset:9216
	ds_read_b128 v[102:105], v137 offset:10368
	ds_read_b128 v[106:109], v137 offset:11520
	ds_read_b128 v[110:113], v137 offset:12672
	ds_read_b128 v[114:117], v137 offset:13824
	ds_read_b128 v[118:121], v137 offset:14976
	ds_read_b128 v[122:125], v137 offset:16128
	ds_read_b128 v[126:129], v137 offset:17280
	v_lshl_add_u64 v[138:139], v[138:139], 0, v[0:1]
	v_lshlrev_b32_e32 v0, 11, v140
	v_lshl_add_u64 v[140:141], v[138:139], 0, v[0:1]
	s_mov_b64 s[50:51], 0
	s_waitcnt lgkmcnt(15)
	global_store_dwordx4 v[140:141], v[66:69], off
	v_or_b32_e32 v140, 0x4000, v0
	v_mov_b32_e32 v141, v1
	v_lshl_add_u64 v[140:141], v[138:139], 0, v[140:141]
	s_waitcnt lgkmcnt(14)
	global_store_dwordx4 v[140:141], v[70:73], off
	v_or_b32_e32 v140, 0x8000, v0
	v_mov_b32_e32 v141, v1
	v_lshl_add_u64 v[140:141], v[138:139], 0, v[140:141]
	s_waitcnt lgkmcnt(13)
	global_store_dwordx4 v[140:141], v[74:77], off
	v_or_b32_e32 v140, 0xc000, v0
	v_mov_b32_e32 v141, v1
	v_lshl_add_u64 v[140:141], v[138:139], 0, v[140:141]
	s_waitcnt lgkmcnt(12)
	global_store_dwordx4 v[140:141], v[78:81], off
	v_or_b32_e32 v140, 0x10000, v0
	v_mov_b32_e32 v141, v1
	v_lshl_add_u64 v[140:141], v[138:139], 0, v[140:141]
	s_waitcnt lgkmcnt(11)
	global_store_dwordx4 v[140:141], v[82:85], off
	v_or_b32_e32 v140, 0x14000, v0
	v_mov_b32_e32 v141, v1
	v_lshl_add_u64 v[140:141], v[138:139], 0, v[140:141]
	s_waitcnt lgkmcnt(10)
	global_store_dwordx4 v[140:141], v[86:89], off
	v_or_b32_e32 v140, 0x18000, v0
	v_mov_b32_e32 v141, v1
	v_lshl_add_u64 v[140:141], v[138:139], 0, v[140:141]
	s_waitcnt lgkmcnt(9)
	global_store_dwordx4 v[140:141], v[90:93], off
	v_or_b32_e32 v140, 0x1c000, v0
	v_mov_b32_e32 v141, v1
	v_lshl_add_u64 v[140:141], v[138:139], 0, v[140:141]
	s_waitcnt lgkmcnt(8)
	global_store_dwordx4 v[140:141], v[94:97], off
	v_or_b32_e32 v140, 0x20000, v0
	v_mov_b32_e32 v141, v1
	v_lshl_add_u64 v[140:141], v[138:139], 0, v[140:141]
	s_waitcnt lgkmcnt(7)
	global_store_dwordx4 v[140:141], v[98:101], off
	v_or_b32_e32 v140, 0x24000, v0
	v_mov_b32_e32 v141, v1
	v_lshl_add_u64 v[140:141], v[138:139], 0, v[140:141]
	s_waitcnt lgkmcnt(6)
	global_store_dwordx4 v[140:141], v[102:105], off
	v_or_b32_e32 v140, 0x28000, v0
	v_mov_b32_e32 v141, v1
	v_lshl_add_u64 v[140:141], v[138:139], 0, v[140:141]
	s_waitcnt lgkmcnt(5)
	global_store_dwordx4 v[140:141], v[106:109], off
	v_or_b32_e32 v140, 0x2c000, v0
	v_mov_b32_e32 v141, v1
	v_lshl_add_u64 v[140:141], v[138:139], 0, v[140:141]
	s_waitcnt lgkmcnt(4)
	global_store_dwordx4 v[140:141], v[110:113], off
	v_or_b32_e32 v140, 0x30000, v0
	v_mov_b32_e32 v141, v1
	v_lshl_add_u64 v[140:141], v[138:139], 0, v[140:141]
	s_waitcnt lgkmcnt(3)
	global_store_dwordx4 v[140:141], v[114:117], off
	v_or_b32_e32 v140, 0x34000, v0
	v_mov_b32_e32 v141, v1
	v_lshl_add_u64 v[140:141], v[138:139], 0, v[140:141]
	s_waitcnt lgkmcnt(2)
	global_store_dwordx4 v[140:141], v[118:121], off
	v_or_b32_e32 v140, 0x38000, v0
	v_mov_b32_e32 v141, v1
	v_lshl_add_u64 v[140:141], v[138:139], 0, v[140:141]
	v_or_b32_e32 v0, 0x3c000, v0
	s_waitcnt lgkmcnt(1)
	global_store_dwordx4 v[140:141], v[122:125], off
	v_lshl_add_u64 v[138:139], v[138:139], 0, v[0:1]
	s_waitcnt lgkmcnt(0)
	global_store_dwordx4 v[138:139], v[126:129], off
	s_waitcnt lgkmcnt(0)
	s_barrier
